# adds: MLA kv-up-projection tile epilogue requests the rope-key rows of all four row groups and both gain vectors once per half; later groups no longer drain vmcnt
# speedup vs baseline: 1.0016x; 1.0016x over previous
.LBB0_363:
	s_andn2_b64 vcc, exec, s[0:1]
	s_cbranch_vccnz .LBB0_414
	s_ashr_i32 s8, s77, 7
	s_bfe_u32 s63, s77, 0x10006
	s_cmpk_gt_u32 s77, 0x7f
	v_and_b32_e32 v140, 15, v156
	s_mov_b64 s[4:5], -1
	s_cselect_b64 s[36:37], -1, 0
	s_cmpk_lt_u32 s77, 0x80
	s_mov_b64 s[0:1], s[24:25]
	s_cbranch_scc1 .LBB0_376
	s_mov_b64 s[40:41], -1
	s_mov_b64 s[6:7], 0
	s_cmp_lt_i32 s8, 3
	s_mov_b64 s[4:5], 0
	s_mov_b64 s[38:39], 0
	s_cbranch_scc1 .LBB0_372
	s_cmp_gt_i32 s8, 4
	s_cbranch_scc0 .LBB0_368
	s_cmp_eq_u32 s8, 5
	s_mov_b64 s[38:39], -1
	s_cselect_b64 s[0:1], -1, 0
	s_andn2_b64 vcc, exec, s[4:5]
	s_cbranch_vccz .LBB0_369
	s_branch .LBB0_370
.Ltramp_9:
	s_branch .LBB0_9
.LBB0_368:
	s_mov_b64 s[0:1], 0

.LBB0_427:
	s_or_b64 exec, exec, s[2:3]
	s_lshl_b64 s[0:1], s[0:1], 7
	s_add_u32 s0, s46, s0
	v_and_b32_e32 v133, 15, v171
	s_addc_u32 s1, s47, s1
	v_lshlrev_b32_e32 v2, 4, v133
	v_ashrrev_i32_e32 v156, 4, v171
	v_lshl_add_u64 v[154:155], s[0:1], 0, v[2:3]
	s_movk_i32 s0, 0x210
	v_mul_lo_u32 v161, v156, s0
	v_add_u32_e32 v168, v161, v2
	s_waitcnt lgkmcnt(0)
	s_barrier
	ds_read_b128 v[140:143], v168
	v_cmp_gt_u32_e32 vcc, 8, v133
	v_mov_b32_e32 v132, 0
	v_ashrrev_i32_e32 v157, 31, v156
	v_mov_b32_e32 v136, 0
	v_mov_b32_e32 v137, 0
	v_mov_b32_e32 v138, 0
	v_mov_b32_e32 v139, 0
	v_mov_b32_e32 v76, 0
	v_mov_b32_e32 v77, 0
	v_mov_b32_e32 v78, 0
	v_mov_b32_e32 v79, 0
	v_mov_b32_e32 v80, 0
	v_mov_b32_e32 v81, 0
	v_mov_b32_e32 v82, 0
	v_mov_b32_e32 v83, 0
	v_mov_b32_e32 v84, 0
	v_mov_b32_e32 v85, 0
	v_mov_b32_e32 v86, 0
	v_mov_b32_e32 v87, 0
	s_and_saveexec_b64 s[0:1], vcc
	s_cbranch_execz .LBB0_429
	v_lshlrev_b64 v[134:135], 7, v[156:157]
	v_lshl_add_u64 v[134:135], v[154:155], 0, v[134:135]
	global_load_dwordx4 v[136:139], v[134:135], off
	global_load_dwordx4 v[76:79], v[134:135], off offset:2048
	v_mov_b32_e32 v88, 0x1000
	v_mov_b32_e32 v89, 0
	v_lshl_add_u64 v[90:91], v[134:135], 0, v[88:89]
	global_load_dwordx4 v[80:83], v[90:91], off
	global_load_dwordx4 v[84:87], v[90:91], off offset:2048

.LBB0_431:
	s_or_b64 exec, exec, s[0:1]
	s_waitcnt lgkmcnt(0)
	v_add_f32_e32 v2, v158, v159
	v_fmamk_f32 v2, v2, 0x3c2aaaab, v1
	v_mul_f32_e32 v158, 0x4b800000, v2
	v_cmp_gt_f32_e64 s[0:1], s29, v2
	s_or_b32 s2, s5, s71
	s_ashr_i32 s3, s2, 31
	v_cndmask_b32_e64 v2, v2, v158, s[0:1]
	v_rsq_f32_e32 v2, v2
	s_lshl_b64 s[2:3], s[2:3], 10
	v_readlane_b32 s8, v253, 26
	v_readlane_b32 s9, v253, 27
	v_mul_f32_e32 v158, 0x45800000, v2
	v_cndmask_b32_e64 v158, v2, v158, s[0:1]
	s_lshl_b32 s0, s4, 8
	s_or_b32 s2, s2, s0
	s_or_b64 s[0:1], s[2:3], s[42:43]
	s_mul_hi_u32 s4, s0, 0xc0
	s_mulk_i32 s3, 0xc0
	s_mul_i32 s2, s0, 0xc0
	s_add_i32 s4, s4, s3
	s_add_u32 s2, s8, s2
	v_pk_mul_f32 v[140:141], v[140:141], v[158:159] op_sel_hi:[1,0]
	s_addc_u32 s3, s9, s4
	s_waitcnt vmcnt(0)
	v_mov_b64_e32 v[68:69], v[144:145]
	v_mov_b64_e32 v[70:71], v[146:147]
	v_mov_b64_e32 v[72:73], v[132:133]
	v_mov_b64_e32 v[74:75], v[134:135]
	v_pk_mul_f32 v[144:145], v[144:145], v[140:141]
	v_pk_mul_f32 v[140:141], v[142:143], v[158:159] op_sel_hi:[1,0]
	s_movk_i32 s4, 0xc0
	v_pk_mul_f32 v[142:143], v[146:147], v[140:141]
	v_mov_b64_e32 v[140:141], s[2:3]
	v_mad_i64_i32 v[140:141], s[4:5], v156, s4, v[140:141]
	v_lshlrev_b32_e32 v2, 1, v172
	v_lshl_add_u64 v[140:141], v[140:141], 0, v[2:3]
	v_cvt_pk_bf16_f32 v144, v144, v145
	v_cvt_pk_bf16_f32 v145, v142, v143
	v_readlane_b32 s10, v253, 28
	v_readlane_b32 s11, v253, 29
	v_readlane_b32 s12, v253, 30
	v_readlane_b32 s13, v253, 31
	v_readlane_b32 s14, v253, 32
	v_readlane_b32 s15, v253, 33
	v_readlane_b32 s16, v253, 34
	v_readlane_b32 s17, v253, 35
	v_readlane_b32 s18, v253, 36
	v_readlane_b32 s19, v253, 37
	v_readlane_b32 s20, v253, 38
	v_readlane_b32 s21, v253, 39
	v_readlane_b32 s22, v253, 40
	v_readlane_b32 s23, v253, 41
	global_store_dwordx2 v[140:141], v[144:145], off
	s_and_saveexec_b64 s[4:5], vcc
	s_cbranch_execz .LBB0_433
	v_mov_b32_e32 v159, v158
	v_pk_mul_f32 v[136:137], v[136:137], v[158:159]
	s_nop 0
	v_pk_mul_f32 v[132:133], v[136:137], v[132:133]
	v_pk_mul_f32 v[136:137], v[138:139], v[158:159]
	v_cvt_pk_bf16_f32 v132, v132, v133
	v_pk_mul_f32 v[134:135], v[136:137], v[134:135]
	s_nop 0
	v_cvt_pk_bf16_f32 v133, v134, v135
	global_store_dwordx2 v[140:141], v[132:133], off offset:128

.LBB0_435:
	s_or_b64 exec, exec, s[0:1]
	v_mov_b64_e32 v[136:137], v[76:77]
	v_mov_b64_e32 v[138:139], v[78:79]
	s_waitcnt lgkmcnt(0)
	v_mul_f32_e32 v133, v141, v141
	v_fmac_f32_e32 v133, v140, v140
	v_pk_mul_f32 v[134:135], v[142:143], v[142:143]
	v_pk_mul_f32 v[144:145], v[136:137], v[136:137]
	v_add_f32_e32 v133, v134, v133
	v_add_f32_e32 v133, v135, v133
	v_add_f32_e32 v133, v133, v144
	v_add_f32_e32 v133, v145, v133
	v_mov_b64_e32 v[144:145], v[68:69]
	v_mov_b64_e32 v[146:147], v[70:71]
	v_pk_mul_f32 v[134:135], v[138:139], v[138:139]
	s_nop 0
	v_add_f32_e32 v133, v134, v133
	v_add_f32_e32 v133, v135, v133
	s_nop 1
	v_mov_b32_e32 v135, 0
	s_waitcnt lgkmcnt(0)
	v_add_f32_dpp v133, v133, v133 quad_perm:[1,0,3,2] row_mask:0xf bank_mask:0xf
	s_nop 1
	s_waitcnt lgkmcnt(0)
	v_add_f32_dpp v133, v133, v133 quad_perm:[2,3,0,1] row_mask:0xf bank_mask:0xf
	s_nop 1
	s_waitcnt lgkmcnt(0)
	v_add_f32_dpp v162, v133, v133 row_half_mirror row_mask:0xf bank_mask:0xf
	ds_bpermute_b32 v163, v167, v162
	v_mov_b32_e32 v133, 0
	v_mov_b32_e32 v134, 0
	s_and_saveexec_b64 s[0:1], vcc
	s_cbranch_execz .LBB0_437
.LBB0_437:
	s_or_b64 exec, exec, s[0:1]
	v_mov_b64_e32 v[132:133], v[72:73]
	v_mov_b64_e32 v[134:135], v[74:75]
	s_waitcnt lgkmcnt(0)
	v_add_f32_e32 v162, v162, v163
	v_fmamk_f32 v162, v162, 0x3c2aaaab, v1
	v_mul_f32_e32 v163, 0x4b800000, v162
	v_cmp_gt_f32_e64 s[0:1], s29, v162
	s_nop 1
	v_cndmask_b32_e64 v162, v162, v163, s[0:1]
	v_rsq_f32_e32 v162, v162
	s_nop 0
	v_mul_f32_e32 v163, 0x45800000, v162
	v_cndmask_b32_e64 v162, v162, v163, s[0:1]
	v_pk_mul_f32 v[140:141], v[140:141], v[162:163] op_sel_hi:[1,0]
	v_pk_mul_f32 v[142:143], v[142:143], v[162:163] op_sel_hi:[1,0]
	v_pk_mul_f32 v[144:145], v[144:145], v[140:141]
	v_mov_b64_e32 v[140:141], s[2:3]
	s_movk_i32 s0, 0xc0
	v_pk_mul_f32 v[142:143], v[146:147], v[142:143]
	v_mad_i64_i32 v[140:141], s[0:1], v160, s0, v[140:141]
	v_lshl_add_u64 v[140:141], v[140:141], 0, v[2:3]
	v_cvt_pk_bf16_f32 v144, v144, v145
	v_cvt_pk_bf16_f32 v145, v142, v143
	global_store_dwordx2 v[140:141], v[144:145], off
	s_and_saveexec_b64 s[0:1], vcc
	s_cbranch_execz .LBB0_439
	v_mov_b32_e32 v163, v162
	v_pk_mul_f32 v[136:137], v[136:137], v[162:163]
	s_nop 0
	v_pk_mul_f32 v[132:133], v[136:137], v[132:133]
	v_pk_mul_f32 v[136:137], v[138:139], v[162:163]
	v_cvt_pk_bf16_f32 v132, v132, v133
	v_pk_mul_f32 v[134:135], v[136:137], v[134:135]
	s_nop 0
	v_cvt_pk_bf16_f32 v133, v134, v135
	global_store_dwordx2 v[140:141], v[132:133], off offset:128

.LBB0_441:
	s_or_b64 exec, exec, s[0:1]
	v_mov_b64_e32 v[136:137], v[80:81]
	v_mov_b64_e32 v[138:139], v[82:83]
	s_waitcnt lgkmcnt(0)
	v_mul_f32_e32 v133, v141, v141
	v_fmac_f32_e32 v133, v140, v140
	v_pk_mul_f32 v[134:135], v[142:143], v[142:143]
	v_pk_mul_f32 v[144:145], v[136:137], v[136:137]
	v_add_f32_e32 v133, v134, v133
	v_add_f32_e32 v133, v135, v133
	v_add_f32_e32 v133, v133, v144
	v_add_f32_e32 v133, v145, v133
	v_mov_b64_e32 v[144:145], v[68:69]
	v_mov_b64_e32 v[146:147], v[70:71]
	v_pk_mul_f32 v[134:135], v[138:139], v[138:139]
	s_nop 0
	v_add_f32_e32 v133, v134, v133
	v_add_f32_e32 v133, v135, v133
	s_nop 1
	v_mov_b32_e32 v135, 0
	s_waitcnt lgkmcnt(0)
	v_add_f32_dpp v133, v133, v133 quad_perm:[1,0,3,2] row_mask:0xf bank_mask:0xf
	s_nop 1
	s_waitcnt lgkmcnt(0)
	v_add_f32_dpp v133, v133, v133 quad_perm:[2,3,0,1] row_mask:0xf bank_mask:0xf
	s_nop 1
	s_waitcnt lgkmcnt(0)
	v_add_f32_dpp v160, v133, v133 row_half_mirror row_mask:0xf bank_mask:0xf
	ds_bpermute_b32 v161, v167, v160
	v_mov_b32_e32 v133, 0
	v_mov_b32_e32 v134, 0
	s_and_saveexec_b64 s[0:1], vcc
	s_cbranch_execz .LBB0_443
.LBB0_443:
	s_or_b64 exec, exec, s[0:1]
	v_mov_b64_e32 v[132:133], v[72:73]
	v_mov_b64_e32 v[134:135], v[74:75]
	s_waitcnt lgkmcnt(0)
	v_add_f32_e32 v160, v160, v161
	v_fmamk_f32 v160, v160, 0x3c2aaaab, v1
	v_mul_f32_e32 v161, 0x4b800000, v160
	v_cmp_gt_f32_e64 s[0:1], s29, v160
	s_nop 1
	v_cndmask_b32_e64 v160, v160, v161, s[0:1]
	v_rsq_f32_e32 v160, v160
	s_nop 0
	v_mul_f32_e32 v161, 0x45800000, v160
	v_cndmask_b32_e64 v160, v160, v161, s[0:1]
	v_pk_mul_f32 v[140:141], v[140:141], v[160:161] op_sel_hi:[1,0]
	v_pk_mul_f32 v[142:143], v[142:143], v[160:161] op_sel_hi:[1,0]
	v_pk_mul_f32 v[144:145], v[144:145], v[140:141]
	v_mov_b64_e32 v[140:141], s[2:3]
	s_movk_i32 s0, 0xc0
	v_pk_mul_f32 v[142:143], v[146:147], v[142:143]
	v_mad_i64_i32 v[140:141], s[0:1], v162, s0, v[140:141]
	v_lshl_add_u64 v[140:141], v[140:141], 0, v[2:3]
	v_cvt_pk_bf16_f32 v144, v144, v145
	v_cvt_pk_bf16_f32 v145, v142, v143
	global_store_dwordx2 v[140:141], v[144:145], off
	s_and_saveexec_b64 s[0:1], vcc
	s_cbranch_execz .LBB0_445
	v_mov_b32_e32 v161, v160
	v_pk_mul_f32 v[136:137], v[136:137], v[160:161]
	s_nop 0
	v_pk_mul_f32 v[132:133], v[136:137], v[132:133]
	v_pk_mul_f32 v[136:137], v[138:139], v[160:161]
	v_cvt_pk_bf16_f32 v132, v132, v133
	v_pk_mul_f32 v[134:135], v[136:137], v[134:135]
	s_nop 0
	v_cvt_pk_bf16_f32 v133, v134, v135
	global_store_dwordx2 v[140:141], v[132:133], off offset:128

.LBB0_447:
	s_or_b64 exec, exec, s[0:1]
	v_mov_b64_e32 v[136:137], v[84:85]
	v_mov_b64_e32 v[138:139], v[86:87]
	s_waitcnt lgkmcnt(0)
	v_mul_f32_e32 v133, v141, v141
	v_fmac_f32_e32 v133, v140, v140
	v_pk_mul_f32 v[134:135], v[142:143], v[142:143]
	v_pk_mul_f32 v[144:145], v[136:137], v[136:137]
	v_add_f32_e32 v133, v134, v133
	v_add_f32_e32 v133, v135, v133
	v_add_f32_e32 v133, v133, v144
	v_add_f32_e32 v133, v145, v133
	v_mov_b64_e32 v[144:145], v[68:69]
	v_mov_b64_e32 v[146:147], v[70:71]
	v_pk_mul_f32 v[134:135], v[138:139], v[138:139]
	s_nop 0
	v_add_f32_e32 v133, v134, v133
	v_add_f32_e32 v133, v135, v133
	s_nop 1
	v_mov_b32_e32 v135, 0
	s_waitcnt lgkmcnt(0)
	v_add_f32_dpp v133, v133, v133 quad_perm:[1,0,3,2] row_mask:0xf bank_mask:0xf
	s_nop 1
	s_waitcnt lgkmcnt(0)
	v_add_f32_dpp v133, v133, v133 quad_perm:[2,3,0,1] row_mask:0xf bank_mask:0xf
	s_nop 1
	s_waitcnt lgkmcnt(0)
	v_add_f32_dpp v162, v133, v133 row_half_mirror row_mask:0xf bank_mask:0xf
	ds_bpermute_b32 v163, v167, v162
	v_mov_b32_e32 v133, 0
	v_mov_b32_e32 v134, 0
	s_and_saveexec_b64 s[0:1], vcc
	s_cbranch_execz .LBB0_449

.LBB0_453:
	s_or_b64 exec, exec, s[4:5]
	s_waitcnt lgkmcnt(0)
	s_barrier
	ds_read_b128 v[12:15], v168
	v_add_u32_e32 v20, 64, v156
	v_mov_b32_e32 v4, 0
	v_ashrrev_i32_e32 v21, 31, v20
	v_mov_b32_e32 v8, 0
	v_mov_b32_e32 v9, 0
	v_mov_b32_e32 v10, 0
	v_mov_b32_e32 v11, 0
	v_mov_b32_e32 v76, 0
	v_mov_b32_e32 v77, 0
	v_mov_b32_e32 v78, 0
	v_mov_b32_e32 v79, 0
	v_mov_b32_e32 v80, 0
	v_mov_b32_e32 v81, 0
	v_mov_b32_e32 v82, 0
	v_mov_b32_e32 v83, 0
	v_mov_b32_e32 v84, 0
	v_mov_b32_e32 v85, 0
	v_mov_b32_e32 v86, 0
	v_mov_b32_e32 v87, 0
	s_and_saveexec_b64 s[0:1], vcc
	s_cbranch_execz .LBB0_455
	v_lshlrev_b64 v[6:7], 7, v[20:21]
	v_lshl_add_u64 v[6:7], v[154:155], 0, v[6:7]
	global_load_dwordx4 v[8:11], v[6:7], off
	global_load_dwordx4 v[76:79], v[6:7], off offset:2048
	v_mov_b32_e32 v88, 0x1000
	v_mov_b32_e32 v89, 0
	v_lshl_add_u64 v[90:91], v[6:7], 0, v[88:89]
	global_load_dwordx4 v[80:83], v[90:91], off
	global_load_dwordx4 v[84:87], v[90:91], off offset:2048

.LBB0_457:
	s_or_b64 exec, exec, s[0:1]
	s_waitcnt lgkmcnt(0)
	v_add_f32_e32 v22, v22, v23
	v_fmamk_f32 v22, v22, 0x3c2aaaab, v1
	v_mul_f32_e32 v23, 0x4b800000, v22
	v_cmp_gt_f32_e64 s[0:1], s29, v22
	s_nop 1
	v_cndmask_b32_e64 v22, v22, v23, s[0:1]
	v_rsq_f32_e32 v22, v22
	s_nop 0
	v_mul_f32_e32 v23, 0x45800000, v22
	v_cndmask_b32_e64 v22, v22, v23, s[0:1]
	v_pk_mul_f32 v[12:13], v[12:13], v[22:23] op_sel_hi:[1,0]
	v_pk_mul_f32 v[14:15], v[14:15], v[22:23] op_sel_hi:[1,0]
	s_waitcnt vmcnt(0)
	v_mov_b64_e32 v[68:69], v[16:17]
	v_mov_b64_e32 v[70:71], v[18:19]
	v_mov_b64_e32 v[72:73], v[4:5]
	v_mov_b64_e32 v[74:75], v[6:7]
	v_pk_mul_f32 v[16:17], v[16:17], v[12:13]
	v_mov_b64_e32 v[12:13], s[2:3]
	s_movk_i32 s0, 0xc0
	v_pk_mul_f32 v[14:15], v[18:19], v[14:15]
	v_mad_i64_i32 v[12:13], s[0:1], v20, s0, v[12:13]
	v_lshl_add_u64 v[12:13], v[12:13], 0, v[2:3]
	v_cvt_pk_bf16_f32 v16, v16, v17
	v_cvt_pk_bf16_f32 v17, v14, v15
	global_store_dwordx2 v[12:13], v[16:17], off
	s_and_saveexec_b64 s[0:1], vcc
	s_cbranch_execz .LBB0_459
	v_mov_b32_e32 v23, v22
	v_pk_mul_f32 v[8:9], v[8:9], v[22:23]
	s_nop 0
	v_pk_mul_f32 v[4:5], v[8:9], v[4:5]
	v_pk_mul_f32 v[8:9], v[10:11], v[22:23]
	v_cvt_pk_bf16_f32 v4, v4, v5
	v_pk_mul_f32 v[6:7], v[8:9], v[6:7]
	s_nop 0
	v_cvt_pk_bf16_f32 v5, v6, v7
	global_store_dwordx2 v[12:13], v[4:5], off offset:128

.LBB0_461:
	s_or_b64 exec, exec, s[0:1]
	v_mov_b64_e32 v[8:9], v[76:77]
	v_mov_b64_e32 v[10:11], v[78:79]
	s_waitcnt lgkmcnt(0)
	v_mul_f32_e32 v5, v13, v13
	v_fmac_f32_e32 v5, v12, v12
	v_pk_mul_f32 v[6:7], v[14:15], v[14:15]
	v_pk_mul_f32 v[16:17], v[8:9], v[8:9]
	v_add_f32_e32 v5, v6, v5
	v_add_f32_e32 v5, v7, v5
	v_add_f32_e32 v5, v5, v16
	v_add_f32_e32 v5, v17, v5
	v_mov_b64_e32 v[16:17], v[68:69]
	v_mov_b64_e32 v[18:19], v[70:71]
	v_pk_mul_f32 v[6:7], v[10:11], v[10:11]
	s_nop 0
	v_add_f32_e32 v5, v6, v5
	v_add_f32_e32 v5, v7, v5
	s_nop 1
	v_mov_b32_e32 v7, 0
	s_waitcnt lgkmcnt(0)
	v_add_f32_dpp v5, v5, v5 quad_perm:[1,0,3,2] row_mask:0xf bank_mask:0xf
	s_nop 1
	s_waitcnt lgkmcnt(0)
	v_add_f32_dpp v5, v5, v5 quad_perm:[2,3,0,1] row_mask:0xf bank_mask:0xf
	s_nop 1
	s_waitcnt lgkmcnt(0)
	v_add_f32_dpp v22, v5, v5 row_half_mirror row_mask:0xf bank_mask:0xf
	ds_bpermute_b32 v23, v167, v22
	v_mov_b32_e32 v5, 0
	v_mov_b32_e32 v6, 0
	s_and_saveexec_b64 s[0:1], vcc
	s_cbranch_execz .LBB0_463
.LBB0_463:
	s_or_b64 exec, exec, s[0:1]
	v_mov_b64_e32 v[4:5], v[72:73]
	v_mov_b64_e32 v[6:7], v[74:75]
	s_waitcnt lgkmcnt(0)
	v_add_f32_e32 v22, v22, v23
	v_fmamk_f32 v22, v22, 0x3c2aaaab, v1
	v_mul_f32_e32 v23, 0x4b800000, v22
	v_cmp_gt_f32_e64 s[0:1], s29, v22
	s_nop 1
	v_cndmask_b32_e64 v22, v22, v23, s[0:1]
	v_rsq_f32_e32 v22, v22
	s_nop 0
	v_mul_f32_e32 v23, 0x45800000, v22
	v_cndmask_b32_e64 v22, v22, v23, s[0:1]
	v_pk_mul_f32 v[12:13], v[12:13], v[22:23] op_sel_hi:[1,0]
	v_pk_mul_f32 v[14:15], v[14:15], v[22:23] op_sel_hi:[1,0]
	v_pk_mul_f32 v[16:17], v[16:17], v[12:13]
	v_mov_b64_e32 v[12:13], s[2:3]
	s_movk_i32 s0, 0xc0
	v_pk_mul_f32 v[14:15], v[18:19], v[14:15]
	v_mad_i64_i32 v[12:13], s[0:1], v20, s0, v[12:13]
	v_lshl_add_u64 v[12:13], v[12:13], 0, v[2:3]
	v_cvt_pk_bf16_f32 v16, v16, v17
	v_cvt_pk_bf16_f32 v17, v14, v15
	global_store_dwordx2 v[12:13], v[16:17], off
	s_and_saveexec_b64 s[0:1], vcc
	s_cbranch_execz .LBB0_465
	v_mov_b32_e32 v23, v22
	v_pk_mul_f32 v[8:9], v[8:9], v[22:23]
	s_nop 0
	v_pk_mul_f32 v[4:5], v[8:9], v[4:5]
	v_pk_mul_f32 v[8:9], v[10:11], v[22:23]
	v_cvt_pk_bf16_f32 v4, v4, v5
	v_pk_mul_f32 v[6:7], v[8:9], v[6:7]
	s_nop 0
	v_cvt_pk_bf16_f32 v5, v6, v7
	global_store_dwordx2 v[12:13], v[4:5], off offset:128

.LBB0_467:
	s_or_b64 exec, exec, s[0:1]
	v_mov_b64_e32 v[8:9], v[80:81]
	v_mov_b64_e32 v[10:11], v[82:83]
	s_waitcnt lgkmcnt(0)
	v_mul_f32_e32 v5, v13, v13
	v_fmac_f32_e32 v5, v12, v12
	v_pk_mul_f32 v[6:7], v[14:15], v[14:15]
	v_pk_mul_f32 v[16:17], v[8:9], v[8:9]
	v_add_f32_e32 v5, v6, v5
	v_add_f32_e32 v5, v7, v5
	v_add_f32_e32 v5, v5, v16
	v_add_f32_e32 v5, v17, v5
	v_mov_b64_e32 v[16:17], v[68:69]
	v_mov_b64_e32 v[18:19], v[70:71]
	v_pk_mul_f32 v[6:7], v[10:11], v[10:11]
	s_nop 0
	v_add_f32_e32 v5, v6, v5
	v_add_f32_e32 v5, v7, v5
	s_nop 1
	v_mov_b32_e32 v7, 0
	s_waitcnt lgkmcnt(0)
	v_add_f32_dpp v5, v5, v5 quad_perm:[1,0,3,2] row_mask:0xf bank_mask:0xf
	s_nop 1
	s_waitcnt lgkmcnt(0)
	v_add_f32_dpp v5, v5, v5 quad_perm:[2,3,0,1] row_mask:0xf bank_mask:0xf
	s_nop 1
	s_waitcnt lgkmcnt(0)
	v_add_f32_dpp v22, v5, v5 row_half_mirror row_mask:0xf bank_mask:0xf
	ds_bpermute_b32 v23, v167, v22
	v_mov_b32_e32 v5, 0
	v_mov_b32_e32 v6, 0
	s_and_saveexec_b64 s[0:1], vcc
	s_cbranch_execz .LBB0_469

.LBB0_473:
	s_or_b64 exec, exec, s[0:1]
	v_mov_b64_e32 v[8:9], v[84:85]
	v_mov_b64_e32 v[10:11], v[86:87]
	s_waitcnt lgkmcnt(0)
	v_mul_f32_e32 v5, v13, v13
	v_fmac_f32_e32 v5, v12, v12
	v_pk_mul_f32 v[6:7], v[14:15], v[14:15]
	v_pk_mul_f32 v[16:17], v[8:9], v[8:9]
	v_add_f32_e32 v5, v6, v5
	v_add_f32_e32 v5, v7, v5
	v_add_f32_e32 v5, v5, v16
	v_add_f32_e32 v5, v17, v5
	v_mov_b64_e32 v[16:17], v[68:69]
	v_mov_b64_e32 v[18:19], v[70:71]
	v_pk_mul_f32 v[6:7], v[10:11], v[10:11]
	s_nop 0
	v_add_f32_e32 v5, v6, v5
	v_add_f32_e32 v5, v7, v5
	s_nop 1
	v_mov_b32_e32 v7, 0
	s_waitcnt lgkmcnt(0)
	v_add_f32_dpp v5, v5, v5 quad_perm:[1,0,3,2] row_mask:0xf bank_mask:0xf
	s_nop 1
	s_waitcnt lgkmcnt(0)
	v_add_f32_dpp v5, v5, v5 quad_perm:[2,3,0,1] row_mask:0xf bank_mask:0xf
	s_nop 1
	s_waitcnt lgkmcnt(0)
	v_add_f32_dpp v22, v5, v5 row_half_mirror row_mask:0xf bank_mask:0xf
	ds_bpermute_b32 v23, v167, v22
	v_mov_b32_e32 v5, 0
	v_mov_b32_e32 v6, 0
	s_and_saveexec_b64 s[0:1], vcc
	s_cbranch_execz .LBB0_475

.LBB0_496:
	s_or_b64 exec, exec, s[2:3]
	s_lshl_b32 s42, s35, 7
	v_readlane_b32 s12, v252, 47
	s_lshl_b32 s1, s42, 7
	v_readlane_b32 s14, v252, 49
	s_add_u32 s2, s14, s1
	v_and_b32_e32 v137, 15, v175
	v_ashrrev_i32_e32 v156, 4, v175
	s_movk_i32 s1, 0x210
	v_lshlrev_b32_e32 v2, 4, v137
	v_mul_lo_u32 v165, v156, s1
	v_add_u32_e32 v172, v165, v2
	s_waitcnt lgkmcnt(0)
	s_barrier
	ds_read_b128 v[132:135], v172
	v_readlane_b32 s15, v252, 50
	s_addc_u32 s3, s15, 0
	v_cmp_gt_u32_e64 s[38:39], 8, v137
	v_lshl_add_u64 v[154:155], s[2:3], 0, v[2:3]
	v_mov_b32_e32 v136, 0
	v_ashrrev_i32_e32 v157, 31, v156
	v_mov_b32_e32 v140, 0
	v_mov_b32_e32 v141, 0
	v_mov_b32_e32 v142, 0
	v_mov_b32_e32 v143, 0
	v_readlane_b32 s13, v252, 48
	v_readlane_b32 s16, v252, 51
	v_readlane_b32 s17, v252, 52
	v_readlane_b32 s18, v252, 53
	v_readlane_b32 s19, v252, 54
	v_mov_b32_e32 v76, 0
	v_mov_b32_e32 v77, 0
	v_mov_b32_e32 v78, 0
	v_mov_b32_e32 v79, 0
	v_mov_b32_e32 v80, 0
	v_mov_b32_e32 v81, 0
	v_mov_b32_e32 v82, 0
	v_mov_b32_e32 v83, 0
	v_mov_b32_e32 v84, 0
	v_mov_b32_e32 v85, 0
	v_mov_b32_e32 v86, 0
	v_mov_b32_e32 v87, 0
	s_and_saveexec_b64 s[2:3], s[38:39]
	s_cbranch_execz .LBB0_498
	v_lshlrev_b64 v[138:139], 7, v[156:157]
	v_lshl_add_u64 v[138:139], v[154:155], 0, v[138:139]
	global_load_dwordx4 v[140:143], v[138:139], off
	global_load_dwordx4 v[76:79], v[138:139], off offset:2048
	v_mov_b32_e32 v88, 0x1000
	v_mov_b32_e32 v89, 0
	v_lshl_add_u64 v[90:91], v[138:139], 0, v[88:89]
	global_load_dwordx4 v[80:83], v[90:91], off
	global_load_dwordx4 v[84:87], v[90:91], off offset:2048

.LBB0_500:
	s_or_b64 exec, exec, s[2:3]
	s_waitcnt lgkmcnt(0)
	v_add_f32_e32 v2, v158, v159
	v_fmamk_f32 v2, v2, 0x3c2aaaab, v1
	v_mul_f32_e32 v158, 0x4b800000, v2
	v_cmp_gt_f32_e32 vcc, s29, v2
	v_readlane_b32 s6, v251, 30
	v_readlane_b32 s7, v251, 31
	v_cndmask_b32_e32 v2, v2, v158, vcc
	v_rsq_f32_e32 v2, v2
	s_cmp_gt_u32 s35, 31
	s_cselect_b64 s[4:5], -1, 0
	s_and_b32 s34, s42, 0x780
	v_mul_f32_e32 v158, 0x45800000, v2
	v_cndmask_b32_e32 v162, v2, v158, vcc
	v_and_b32_e32 v2, 7, v175
	v_cmp_gt_u32_e64 s[2:3], 4, v2
	v_lshlrev_b32_e32 v2, 4, v175
	v_and_b32_e32 v2, 16, v2
	v_lshl_add_u64 v[158:159], s[6:7], 0, v[2:3]
	v_readlane_b32 s6, v251, 32
	v_readlane_b32 s7, v251, 33
	v_pk_mul_f32 v[140:141], v[140:141], v[162:163] op_sel_hi:[1,0]
	s_cmp_lt_u32 s35, 32
	v_lshl_add_u64 v[160:161], s[6:7], 0, v[2:3]
	v_and_b32_e32 v2, 2, v175
	s_waitcnt vmcnt(0)
	v_mov_b64_e32 v[68:69], v[144:145]
	v_mov_b64_e32 v[70:71], v[146:147]
	v_mov_b64_e32 v[72:73], v[136:137]
	v_mov_b64_e32 v[74:75], v[138:139]
	v_pk_mul_f32 v[136:137], v[140:141], v[136:137]
	v_pk_mul_f32 v[140:141], v[142:143], v[162:163] op_sel_hi:[1,0]
	v_cmp_eq_u32_e64 s[40:41], 0, v2
	v_and_b32_e32 v177, 63, v156
	v_pk_mul_f32 v[138:139], v[140:141], v[138:139]
	s_cbranch_scc1 .LBB0_502
	s_and_b32 s1, s42, 0x80
	s_and_b64 s[6:7], s[4:5], exec
	s_cselect_b32 s1, s34, s1
	v_add_u32_e32 v2, s1, v156
	v_ashrrev_i32_e32 v2, 6, v2
	v_cndmask_b32_e64 v2, v177, v2, s[2:3]
	v_lshlrev_b32_e32 v140, 3, v2
	v_ashrrev_i32_e32 v141, 31, v140
	v_lshlrev_b64 v[140:141], 2, v[140:141]
	v_lshl_add_u64 v[166:167], v[158:159], 0, v[140:141]
	v_lshl_add_u64 v[140:141], v[160:161], 0, v[140:141]
	global_load_dwordx4 v[140:143], v[140:141], off
	s_nop 0
	global_load_dwordx4 v[178:181], v[166:167], off
	ds_bpermute_b32 v2, v168, v137
	ds_bpermute_b32 v164, v168, v138
	ds_bpermute_b32 v167, v168, v139
	ds_bpermute_b32 v163, v168, v136
	v_mov_b32_e32 v166, v139
	s_waitcnt lgkmcnt(3)
	v_cndmask_b32_e64 v183, v2, -v2, s[40:41]
	s_waitcnt lgkmcnt(2)
	v_cndmask_b32_e64 v2, v164, -v164, s[40:41]
	s_waitcnt lgkmcnt(1)
	v_cndmask_b32_e64 v167, v167, -v167, s[40:41]
	s_waitcnt lgkmcnt(0)
	v_cndmask_b32_e64 v182, v163, -v163, s[40:41]
	s_waitcnt vmcnt(1)
	v_pk_mul_f32 v[140:141], v[140:141], v[182:183]
	s_waitcnt vmcnt(0)
	v_mul_f32_e32 v138, v138, v180
	v_mul_f32_e32 v180, v142, v2
	v_mov_b32_e32 v142, v181
	v_pk_mul_f32 v[142:143], v[166:167], v[142:143]
	v_pk_fma_f32 v[136:137], v[136:137], v[178:179], v[140:141]
	v_mov_b32_e32 v139, v142
	v_mov_b32_e32 v181, v143
	v_pk_add_f32 v[138:139], v[138:139], v[180:181]

.LBB0_506:
	s_or_b64 exec, exec, s[0:1]
	v_mov_b64_e32 v[140:141], v[76:77]
	v_mov_b64_e32 v[142:143], v[78:79]
	s_waitcnt lgkmcnt(0)
	v_mul_f32_e32 v137, v133, v133
	v_fmac_f32_e32 v137, v132, v132
	v_pk_mul_f32 v[138:139], v[134:135], v[134:135]
	v_pk_mul_f32 v[144:145], v[140:141], v[140:141]
	v_add_f32_e32 v137, v138, v137
	v_add_f32_e32 v137, v139, v137
	v_add_f32_e32 v137, v137, v144
	v_add_f32_e32 v137, v145, v137
	v_mov_b64_e32 v[144:145], v[68:69]
	v_mov_b64_e32 v[146:147], v[70:71]
	v_pk_mul_f32 v[138:139], v[142:143], v[142:143]
	s_nop 0
	v_add_f32_e32 v137, v138, v137
	v_add_f32_e32 v137, v139, v137
	s_nop 1
	v_mov_b32_e32 v139, 0
	s_waitcnt lgkmcnt(0)
	v_add_f32_dpp v137, v137, v137 quad_perm:[1,0,3,2] row_mask:0xf bank_mask:0xf
	s_nop 1
	s_waitcnt lgkmcnt(0)
	v_add_f32_dpp v137, v137, v137 quad_perm:[2,3,0,1] row_mask:0xf bank_mask:0xf
	s_nop 1
	s_waitcnt lgkmcnt(0)
	v_add_f32_dpp v166, v137, v137 row_half_mirror row_mask:0xf bank_mask:0xf
	ds_bpermute_b32 v167, v171, v166
	v_mov_b32_e32 v137, 0
	v_mov_b32_e32 v138, 0
	s_and_saveexec_b64 s[0:1], s[38:39]
	s_movk_i32 s36, 0x1fff
	s_cbranch_execz .LBB0_508
.LBB0_508:
	s_or_b64 exec, exec, s[0:1]
	v_mov_b64_e32 v[136:137], v[72:73]
	v_mov_b64_e32 v[138:139], v[74:75]
	s_waitcnt lgkmcnt(0)
	v_add_f32_e32 v166, v166, v167
	v_fmamk_f32 v166, v166, 0x3c2aaaab, v1
	v_mul_f32_e32 v167, 0x4b800000, v166
	v_cmp_gt_f32_e32 vcc, s29, v166
	v_and_b32_e32 v179, 63, v164
	s_nop 0
	v_cndmask_b32_e32 v166, v166, v167, vcc
	v_rsq_f32_e32 v166, v166
	s_nop 0
	v_mul_f32_e32 v167, 0x45800000, v166
	v_cndmask_b32_e32 v166, v166, v167, vcc
	v_pk_mul_f32 v[140:141], v[140:141], v[166:167] op_sel_hi:[1,0]
	v_pk_mul_f32 v[142:143], v[142:143], v[166:167] op_sel_hi:[1,0]
	v_pk_mul_f32 v[136:137], v[140:141], v[136:137]
	v_cndmask_b32_e64 v140, 0, 1, s[4:5]
	v_cmp_ne_u32_e64 s[0:1], 1, v140
	s_andn2_b64 vcc, exec, s[4:5]
	v_pk_mul_f32 v[138:139], v[142:143], v[138:139]
	s_cbranch_vccnz .LBB0_510
	v_add_u32_e32 v140, s34, v164
	v_ashrrev_i32_e32 v140, 6, v140
	v_cndmask_b32_e64 v140, v179, v140, s[2:3]
	v_lshlrev_b32_e32 v140, 3, v140
	v_ashrrev_i32_e32 v141, 31, v140
	v_lshlrev_b64 v[140:141], 2, v[140:141]
	v_lshl_add_u64 v[180:181], v[158:159], 0, v[140:141]
	v_lshl_add_u64 v[140:141], v[160:161], 0, v[140:141]
	global_load_dwordx4 v[140:143], v[140:141], off
	s_nop 0
	global_load_dwordx4 v[180:183], v[180:181], off
	ds_bpermute_b32 v185, v168, v138
	ds_bpermute_b32 v188, v168, v139
	ds_bpermute_b32 v167, v168, v137
	ds_bpermute_b32 v178, v168, v136
	v_mov_b32_e32 v184, v139
	s_waitcnt lgkmcnt(3)
	v_cndmask_b32_e64 v139, v185, -v185, s[40:41]
	s_waitcnt lgkmcnt(2)
	v_cndmask_b32_e64 v185, v188, -v188, s[40:41]
	s_waitcnt lgkmcnt(1)
	v_cndmask_b32_e64 v187, v167, -v167, s[40:41]
	s_waitcnt lgkmcnt(0)
	v_cndmask_b32_e64 v186, v178, -v178, s[40:41]
	s_waitcnt vmcnt(1)
	v_pk_mul_f32 v[140:141], v[140:141], v[186:187]
	s_waitcnt vmcnt(0)
	v_mul_f32_e32 v138, v138, v182
	v_mul_f32_e32 v182, v142, v139
	v_mov_b32_e32 v142, v183
	v_pk_mul_f32 v[142:143], v[184:185], v[142:143]
	v_pk_fma_f32 v[136:137], v[136:137], v[180:181], v[140:141]
	v_mov_b32_e32 v139, v142
	v_mov_b32_e32 v183, v143
	v_pk_add_f32 v[138:139], v[138:139], v[182:183]

.LBB0_514:
	s_or_b64 exec, exec, s[4:5]
	v_mov_b64_e32 v[140:141], v[80:81]
	v_mov_b64_e32 v[142:143], v[82:83]
	s_waitcnt lgkmcnt(0)
	v_mul_f32_e32 v137, v133, v133
	v_fmac_f32_e32 v137, v132, v132
	v_pk_mul_f32 v[138:139], v[134:135], v[134:135]
	v_pk_mul_f32 v[144:145], v[140:141], v[140:141]
	v_add_f32_e32 v137, v138, v137
	v_add_f32_e32 v137, v139, v137
	v_add_f32_e32 v137, v137, v144
	v_add_f32_e32 v137, v145, v137
	v_mov_b64_e32 v[144:145], v[68:69]
	v_mov_b64_e32 v[146:147], v[70:71]
	v_pk_mul_f32 v[138:139], v[142:143], v[142:143]
	s_nop 0
	v_add_f32_e32 v137, v138, v137
	v_add_f32_e32 v137, v139, v137
	s_nop 1
	v_mov_b32_e32 v139, 0
	s_waitcnt lgkmcnt(0)
	v_add_f32_dpp v137, v137, v137 quad_perm:[1,0,3,2] row_mask:0xf bank_mask:0xf
	s_nop 1
	s_waitcnt lgkmcnt(0)
	v_add_f32_dpp v137, v137, v137 quad_perm:[2,3,0,1] row_mask:0xf bank_mask:0xf
	s_nop 1
	s_waitcnt lgkmcnt(0)
	v_add_f32_dpp v164, v137, v137 row_half_mirror row_mask:0xf bank_mask:0xf
	ds_bpermute_b32 v165, v171, v164
	v_mov_b32_e32 v137, 0
	v_mov_b32_e32 v138, 0
	s_and_saveexec_b64 s[4:5], s[38:39]
	s_cbranch_execz .LBB0_516
.LBB0_516:
	s_or_b64 exec, exec, s[4:5]
	v_mov_b64_e32 v[136:137], v[72:73]
	v_mov_b64_e32 v[138:139], v[74:75]
	s_waitcnt lgkmcnt(0)
	v_add_f32_e32 v164, v164, v165
	v_fmamk_f32 v164, v164, 0x3c2aaaab, v1
	v_mul_f32_e32 v165, 0x4b800000, v164
	v_cmp_gt_f32_e32 vcc, s29, v164
	v_xor_b32_e32 v178, 32, v177
	s_nop 0
	v_cndmask_b32_e32 v164, v164, v165, vcc
	v_rsq_f32_e32 v164, v164
	s_nop 0
	v_mul_f32_e32 v165, 0x45800000, v164
	v_cndmask_b32_e32 v164, v164, v165, vcc
	v_pk_mul_f32 v[140:141], v[140:141], v[164:165] op_sel_hi:[1,0]
	v_pk_mul_f32 v[142:143], v[142:143], v[164:165] op_sel_hi:[1,0]
	v_pk_mul_f32 v[136:137], v[140:141], v[136:137]
	s_and_b64 vcc, exec, s[0:1]
	v_pk_mul_f32 v[138:139], v[142:143], v[138:139]
	s_cbranch_vccnz .LBB0_518
	v_add_u32_e32 v140, s34, v166
	v_ashrrev_i32_e32 v140, 6, v140
	v_cndmask_b32_e64 v140, v178, v140, s[2:3]
	v_lshlrev_b32_e32 v140, 3, v140
	v_ashrrev_i32_e32 v141, 31, v140
	v_lshlrev_b64 v[140:141], 2, v[140:141]
	v_lshl_add_u64 v[180:181], v[158:159], 0, v[140:141]
	v_lshl_add_u64 v[140:141], v[160:161], 0, v[140:141]
	global_load_dwordx4 v[140:143], v[140:141], off
	s_nop 0
	global_load_dwordx4 v[180:183], v[180:181], off
	ds_bpermute_b32 v185, v168, v138
	ds_bpermute_b32 v188, v168, v139
	ds_bpermute_b32 v165, v168, v137
	ds_bpermute_b32 v176, v168, v136
	v_mov_b32_e32 v184, v139
	s_waitcnt lgkmcnt(3)
	v_cndmask_b32_e64 v139, v185, -v185, s[40:41]
	s_waitcnt lgkmcnt(2)
	v_cndmask_b32_e64 v185, v188, -v188, s[40:41]
	s_waitcnt lgkmcnt(1)
	v_cndmask_b32_e64 v187, v165, -v165, s[40:41]
	s_waitcnt lgkmcnt(0)
	v_cndmask_b32_e64 v186, v176, -v176, s[40:41]
	s_waitcnt vmcnt(1)
	v_pk_mul_f32 v[140:141], v[140:141], v[186:187]
	s_waitcnt vmcnt(0)
	v_mul_f32_e32 v138, v138, v182
	v_mul_f32_e32 v182, v142, v139
	v_mov_b32_e32 v142, v183
	v_pk_mul_f32 v[142:143], v[184:185], v[142:143]
	v_pk_fma_f32 v[136:137], v[136:137], v[180:181], v[140:141]
	v_mov_b32_e32 v139, v142
	v_mov_b32_e32 v183, v143
	v_pk_add_f32 v[138:139], v[138:139], v[182:183]

.LBB0_522:
	s_or_b64 exec, exec, s[4:5]
	v_mov_b64_e32 v[140:141], v[84:85]
	v_mov_b64_e32 v[142:143], v[86:87]
	s_waitcnt lgkmcnt(0)
	v_mul_f32_e32 v137, v133, v133
	v_fmac_f32_e32 v137, v132, v132
	v_pk_mul_f32 v[138:139], v[134:135], v[134:135]
	v_pk_mul_f32 v[144:145], v[140:141], v[140:141]
	v_add_f32_e32 v137, v138, v137
	v_add_f32_e32 v137, v139, v137
	v_add_f32_e32 v137, v137, v144
	v_add_f32_e32 v137, v145, v137
	v_mov_b64_e32 v[144:145], v[68:69]
	v_mov_b64_e32 v[146:147], v[70:71]
	v_pk_mul_f32 v[138:139], v[142:143], v[142:143]
	s_nop 0
	v_add_f32_e32 v137, v138, v137
	v_add_f32_e32 v137, v139, v137
	s_nop 1
	v_mov_b32_e32 v139, 0
	s_waitcnt lgkmcnt(0)
	v_add_f32_dpp v137, v137, v137 quad_perm:[1,0,3,2] row_mask:0xf bank_mask:0xf
	s_nop 1
	s_waitcnt lgkmcnt(0)
	v_add_f32_dpp v137, v137, v137 quad_perm:[2,3,0,1] row_mask:0xf bank_mask:0xf
	s_nop 1
	s_waitcnt lgkmcnt(0)
	v_add_f32_dpp v166, v137, v137 row_half_mirror row_mask:0xf bank_mask:0xf
	ds_bpermute_b32 v167, v171, v166
	v_mov_b32_e32 v137, 0
	v_mov_b32_e32 v138, 0
	s_and_saveexec_b64 s[4:5], s[38:39]
	s_cbranch_execz .LBB0_524
.LBB0_524:
	s_or_b64 exec, exec, s[4:5]
	v_mov_b64_e32 v[136:137], v[72:73]
	v_mov_b64_e32 v[138:139], v[74:75]
	s_waitcnt lgkmcnt(0)
	v_add_f32_e32 v166, v166, v167
	v_fmamk_f32 v166, v166, 0x3c2aaaab, v1
	v_mul_f32_e32 v167, 0x4b800000, v166
	v_cmp_gt_f32_e32 vcc, s29, v166
	v_and_b32_e32 v176, 63, v164
	s_nop 0
	v_cndmask_b32_e32 v166, v166, v167, vcc
	v_rsq_f32_e32 v166, v166
	s_nop 0
	v_mul_f32_e32 v167, 0x45800000, v166
	v_cndmask_b32_e32 v166, v166, v167, vcc
	v_pk_mul_f32 v[140:141], v[140:141], v[166:167] op_sel_hi:[1,0]
	v_pk_mul_f32 v[142:143], v[142:143], v[166:167] op_sel_hi:[1,0]
	v_pk_mul_f32 v[136:137], v[140:141], v[136:137]
	s_and_b64 vcc, exec, s[0:1]
	v_pk_mul_f32 v[138:139], v[142:143], v[138:139]
	s_cbranch_vccnz .LBB0_526
	v_add_u32_e32 v140, s34, v164
	v_ashrrev_i32_e32 v140, 6, v140
	v_cndmask_b32_e64 v140, v176, v140, s[2:3]
	v_lshlrev_b32_e32 v140, 3, v140
	v_ashrrev_i32_e32 v141, 31, v140
	v_lshlrev_b64 v[140:141], 2, v[140:141]
	v_lshl_add_u64 v[180:181], v[158:159], 0, v[140:141]
	v_lshl_add_u64 v[140:141], v[160:161], 0, v[140:141]
	global_load_dwordx4 v[140:143], v[140:141], off
	s_nop 0
	global_load_dwordx4 v[180:183], v[180:181], off
	ds_bpermute_b32 v188, v168, v138
	ds_bpermute_b32 v185, v168, v136
	ds_bpermute_b32 v189, v168, v139
	ds_bpermute_b32 v167, v168, v137
	v_mov_b32_e32 v184, v139
	s_waitcnt lgkmcnt(3)
	v_cndmask_b32_e64 v139, v188, -v188, s[40:41]
	s_waitcnt lgkmcnt(2)
	v_cndmask_b32_e64 v186, v185, -v185, s[40:41]
	s_waitcnt lgkmcnt(1)
	v_cndmask_b32_e64 v185, v189, -v189, s[40:41]
	s_waitcnt lgkmcnt(0)
	v_cndmask_b32_e64 v187, v167, -v167, s[40:41]
	s_waitcnt vmcnt(1)
	v_pk_mul_f32 v[140:141], v[140:141], v[186:187]
	s_waitcnt vmcnt(0)
	v_mul_f32_e32 v138, v138, v182
	v_mul_f32_e32 v182, v142, v139
	v_mov_b32_e32 v142, v183
	v_pk_mul_f32 v[142:143], v[184:185], v[142:143]
	v_pk_fma_f32 v[136:137], v[136:137], v[180:181], v[140:141]
	v_mov_b32_e32 v139, v142
	v_mov_b32_e32 v183, v143
	v_pk_add_f32 v[138:139], v[138:139], v[182:183]

.LBB0_530:
	s_or_b64 exec, exec, s[4:5]
	s_waitcnt lgkmcnt(0)
	s_barrier
	ds_read_b128 v[4:7], v172
	v_add_u32_e32 v20, 64, v156
	v_mov_b32_e32 v8, 0
	v_ashrrev_i32_e32 v21, 31, v20
	v_mov_b32_e32 v12, 0
	v_mov_b32_e32 v13, 0
	v_mov_b32_e32 v14, 0
	v_mov_b32_e32 v15, 0
	v_mov_b32_e32 v76, 0
	v_mov_b32_e32 v77, 0
	v_mov_b32_e32 v78, 0
	v_mov_b32_e32 v79, 0
	v_mov_b32_e32 v80, 0
	v_mov_b32_e32 v81, 0
	v_mov_b32_e32 v82, 0
	v_mov_b32_e32 v83, 0
	v_mov_b32_e32 v84, 0
	v_mov_b32_e32 v85, 0
	v_mov_b32_e32 v86, 0
	v_mov_b32_e32 v87, 0
	s_and_saveexec_b64 s[4:5], s[38:39]
	s_cbranch_execz .LBB0_532
	v_lshlrev_b64 v[10:11], 7, v[20:21]
	v_lshl_add_u64 v[10:11], v[154:155], 0, v[10:11]
	global_load_dwordx4 v[12:15], v[10:11], off
	global_load_dwordx4 v[76:79], v[10:11], off offset:2048
	v_mov_b32_e32 v88, 0x1000
	v_mov_b32_e32 v89, 0
	v_lshl_add_u64 v[90:91], v[10:11], 0, v[88:89]
	global_load_dwordx4 v[80:83], v[90:91], off
	global_load_dwordx4 v[84:87], v[90:91], off offset:2048

.LBB0_534:
	s_or_b64 exec, exec, s[4:5]
	s_waitcnt lgkmcnt(0)
	v_add_f32_e32 v22, v22, v23
	v_fmamk_f32 v22, v22, 0x3c2aaaab, v1
	v_mul_f32_e32 v23, 0x4b800000, v22
	v_cmp_gt_f32_e64 s[4:5], s29, v22
	s_and_b64 vcc, exec, s[0:1]
	s_nop 0
	v_cndmask_b32_e64 v22, v22, v23, s[4:5]
	v_rsq_f32_e32 v22, v22
	s_nop 0
	v_mul_f32_e32 v23, 0x45800000, v22
	v_cndmask_b32_e64 v22, v22, v23, s[4:5]
	v_pk_mul_f32 v[12:13], v[12:13], v[22:23] op_sel_hi:[1,0]
	v_pk_mul_f32 v[14:15], v[14:15], v[22:23] op_sel_hi:[1,0]
	s_waitcnt vmcnt(0)
	v_mov_b64_e32 v[68:69], v[16:17]
	v_mov_b64_e32 v[70:71], v[18:19]
	v_mov_b64_e32 v[72:73], v[8:9]
	v_mov_b64_e32 v[74:75], v[10:11]
	v_pk_mul_f32 v[8:9], v[12:13], v[8:9]
	v_pk_mul_f32 v[10:11], v[14:15], v[10:11]
	s_cbranch_vccnz .LBB0_536
	v_add_u32_e32 v12, s34, v20
	v_ashrrev_i32_e32 v12, 6, v12
	v_cndmask_b32_e64 v12, v177, v12, s[2:3]
	v_lshlrev_b32_e32 v12, 3, v12
	v_ashrrev_i32_e32 v13, 31, v12
	v_lshlrev_b64 v[12:13], 2, v[12:13]
	v_lshl_add_u64 v[24:25], v[158:159], 0, v[12:13]
	v_lshl_add_u64 v[12:13], v[160:161], 0, v[12:13]
	global_load_dwordx4 v[12:15], v[12:13], off
	s_nop 0
	global_load_dwordx4 v[24:27], v[24:25], off
	ds_bpermute_b32 v32, v168, v10
	ds_bpermute_b32 v29, v168, v8
	ds_bpermute_b32 v33, v168, v11
	ds_bpermute_b32 v23, v168, v9
	v_mov_b32_e32 v28, v11
	s_waitcnt lgkmcnt(3)
	v_cndmask_b32_e64 v11, v32, -v32, s[40:41]
	s_waitcnt lgkmcnt(2)
	v_cndmask_b32_e64 v30, v29, -v29, s[40:41]
	s_waitcnt lgkmcnt(1)
	v_cndmask_b32_e64 v29, v33, -v33, s[40:41]
	s_waitcnt lgkmcnt(0)
	v_cndmask_b32_e64 v31, v23, -v23, s[40:41]
	s_waitcnt vmcnt(1)
	v_pk_mul_f32 v[12:13], v[12:13], v[30:31]
	s_waitcnt vmcnt(0)
	v_mul_f32_e32 v10, v10, v26
	v_mul_f32_e32 v26, v14, v11
	v_mov_b32_e32 v14, v27
	v_pk_mul_f32 v[14:15], v[28:29], v[14:15]
	v_pk_fma_f32 v[8:9], v[8:9], v[24:25], v[12:13]
	v_mov_b32_e32 v11, v14
	v_mov_b32_e32 v27, v15
	v_pk_add_f32 v[10:11], v[10:11], v[26:27]

.LBB0_540:
	s_or_b64 exec, exec, s[4:5]
	v_mov_b64_e32 v[12:13], v[76:77]
	v_mov_b64_e32 v[14:15], v[78:79]
	s_waitcnt lgkmcnt(0)
	v_mul_f32_e32 v9, v5, v5
	v_fmac_f32_e32 v9, v4, v4
	v_pk_mul_f32 v[10:11], v[6:7], v[6:7]
	v_pk_mul_f32 v[16:17], v[12:13], v[12:13]
	v_add_f32_e32 v9, v10, v9
	v_add_f32_e32 v9, v11, v9
	v_add_f32_e32 v9, v9, v16
	v_add_f32_e32 v9, v17, v9
	v_mov_b64_e32 v[16:17], v[68:69]
	v_mov_b64_e32 v[18:19], v[70:71]
	v_pk_mul_f32 v[10:11], v[14:15], v[14:15]
	s_nop 0
	v_add_f32_e32 v9, v10, v9
	v_add_f32_e32 v9, v11, v9
	s_nop 1
	v_mov_b32_e32 v11, 0
	s_waitcnt lgkmcnt(0)
	v_add_f32_dpp v9, v9, v9 quad_perm:[1,0,3,2] row_mask:0xf bank_mask:0xf
	s_nop 1
	s_waitcnt lgkmcnt(0)
	v_add_f32_dpp v9, v9, v9 quad_perm:[2,3,0,1] row_mask:0xf bank_mask:0xf
	s_nop 1
	s_waitcnt lgkmcnt(0)
	v_add_f32_dpp v22, v9, v9 row_half_mirror row_mask:0xf bank_mask:0xf
	ds_bpermute_b32 v23, v171, v22
	v_mov_b32_e32 v9, 0
	v_mov_b32_e32 v10, 0
	s_and_saveexec_b64 s[4:5], s[38:39]
	s_cbranch_execz .LBB0_542
.LBB0_542:
	s_or_b64 exec, exec, s[4:5]
	v_mov_b64_e32 v[8:9], v[72:73]
	v_mov_b64_e32 v[10:11], v[74:75]
	s_waitcnt lgkmcnt(0)
	v_add_f32_e32 v22, v22, v23
	v_fmamk_f32 v22, v22, 0x3c2aaaab, v1
	v_mul_f32_e32 v23, 0x4b800000, v22
	v_cmp_gt_f32_e64 s[4:5], s29, v22
	s_and_b64 vcc, exec, s[0:1]
	s_nop 0
	v_cndmask_b32_e64 v22, v22, v23, s[4:5]
	v_rsq_f32_e32 v22, v22
	s_nop 0
	v_mul_f32_e32 v23, 0x45800000, v22
	v_cndmask_b32_e64 v22, v22, v23, s[4:5]
	v_pk_mul_f32 v[12:13], v[12:13], v[22:23] op_sel_hi:[1,0]
	v_pk_mul_f32 v[14:15], v[14:15], v[22:23] op_sel_hi:[1,0]
	v_pk_mul_f32 v[8:9], v[12:13], v[8:9]
	v_pk_mul_f32 v[10:11], v[14:15], v[10:11]
	s_cbranch_vccnz .LBB0_544
	v_add_u32_e32 v12, s34, v20
	v_ashrrev_i32_e32 v12, 6, v12
	v_cndmask_b32_e64 v12, v179, v12, s[2:3]
	v_lshlrev_b32_e32 v12, 3, v12
	v_ashrrev_i32_e32 v13, 31, v12
	v_lshlrev_b64 v[12:13], 2, v[12:13]
	v_lshl_add_u64 v[24:25], v[158:159], 0, v[12:13]
	v_lshl_add_u64 v[12:13], v[160:161], 0, v[12:13]
	global_load_dwordx4 v[12:15], v[12:13], off
	s_nop 0
	global_load_dwordx4 v[24:27], v[24:25], off
	ds_bpermute_b32 v32, v168, v10
	ds_bpermute_b32 v29, v168, v8
	ds_bpermute_b32 v33, v168, v11
	ds_bpermute_b32 v23, v168, v9
	v_mov_b32_e32 v28, v11
	s_waitcnt lgkmcnt(3)
	v_cndmask_b32_e64 v11, v32, -v32, s[40:41]
	s_waitcnt lgkmcnt(2)
	v_cndmask_b32_e64 v30, v29, -v29, s[40:41]
	s_waitcnt lgkmcnt(1)
	v_cndmask_b32_e64 v29, v33, -v33, s[40:41]
	s_waitcnt lgkmcnt(0)
	v_cndmask_b32_e64 v31, v23, -v23, s[40:41]
	s_waitcnt vmcnt(1)
	v_pk_mul_f32 v[12:13], v[12:13], v[30:31]
	s_waitcnt vmcnt(0)
	v_mul_f32_e32 v10, v10, v26
	v_mul_f32_e32 v26, v14, v11
	v_mov_b32_e32 v14, v27
	v_pk_mul_f32 v[14:15], v[28:29], v[14:15]
	v_pk_fma_f32 v[8:9], v[8:9], v[24:25], v[12:13]
	v_mov_b32_e32 v11, v14
	v_mov_b32_e32 v27, v15
	v_pk_add_f32 v[10:11], v[10:11], v[26:27]

.LBB0_548:
	s_or_b64 exec, exec, s[4:5]
	v_mov_b64_e32 v[12:13], v[80:81]
	v_mov_b64_e32 v[14:15], v[82:83]
	s_waitcnt lgkmcnt(0)
	v_mul_f32_e32 v9, v5, v5
	v_fmac_f32_e32 v9, v4, v4
	v_pk_mul_f32 v[10:11], v[6:7], v[6:7]
	v_pk_mul_f32 v[16:17], v[12:13], v[12:13]
	v_add_f32_e32 v9, v10, v9
	v_add_f32_e32 v9, v11, v9
	v_add_f32_e32 v9, v9, v16
	v_add_f32_e32 v9, v17, v9
	v_mov_b64_e32 v[16:17], v[68:69]
	v_mov_b64_e32 v[18:19], v[70:71]
	v_pk_mul_f32 v[10:11], v[14:15], v[14:15]
	s_nop 0
	v_add_f32_e32 v9, v10, v9
	v_add_f32_e32 v9, v11, v9
	s_nop 1
	v_mov_b32_e32 v11, 0
	s_waitcnt lgkmcnt(0)
	v_add_f32_dpp v9, v9, v9 quad_perm:[1,0,3,2] row_mask:0xf bank_mask:0xf
	s_nop 1
	s_waitcnt lgkmcnt(0)
	v_add_f32_dpp v9, v9, v9 quad_perm:[2,3,0,1] row_mask:0xf bank_mask:0xf
	s_nop 1
	s_waitcnt lgkmcnt(0)
	v_add_f32_dpp v22, v9, v9 row_half_mirror row_mask:0xf bank_mask:0xf
	ds_bpermute_b32 v23, v171, v22
	v_mov_b32_e32 v9, 0
	v_mov_b32_e32 v10, 0
	s_and_saveexec_b64 s[4:5], s[38:39]
	s_cbranch_execz .LBB0_550
.LBB0_550:
	s_or_b64 exec, exec, s[4:5]
	v_mov_b64_e32 v[8:9], v[72:73]
	v_mov_b64_e32 v[10:11], v[74:75]
	s_waitcnt lgkmcnt(0)
	v_add_f32_e32 v22, v22, v23
	v_fmamk_f32 v22, v22, 0x3c2aaaab, v1
	v_mul_f32_e32 v23, 0x4b800000, v22
	v_cmp_gt_f32_e64 s[4:5], s29, v22
	s_and_b64 vcc, exec, s[0:1]
	s_nop 0
	v_cndmask_b32_e64 v22, v22, v23, s[4:5]
	v_rsq_f32_e32 v22, v22
	s_nop 0
	v_mul_f32_e32 v23, 0x45800000, v22
	v_cndmask_b32_e64 v22, v22, v23, s[4:5]
	v_pk_mul_f32 v[12:13], v[12:13], v[22:23] op_sel_hi:[1,0]
	v_pk_mul_f32 v[14:15], v[14:15], v[22:23] op_sel_hi:[1,0]
	v_pk_mul_f32 v[8:9], v[12:13], v[8:9]
	v_pk_mul_f32 v[10:11], v[14:15], v[10:11]
	s_cbranch_vccnz .LBB0_552
	v_add_u32_e32 v12, s34, v20
	v_ashrrev_i32_e32 v12, 6, v12
	v_cndmask_b32_e64 v12, v178, v12, s[2:3]
	v_lshlrev_b32_e32 v12, 3, v12
	v_ashrrev_i32_e32 v13, 31, v12
	v_lshlrev_b64 v[12:13], 2, v[12:13]
	v_lshl_add_u64 v[24:25], v[158:159], 0, v[12:13]
	v_lshl_add_u64 v[12:13], v[160:161], 0, v[12:13]
	global_load_dwordx4 v[12:15], v[12:13], off
	s_nop 0
	global_load_dwordx4 v[24:27], v[24:25], off
	ds_bpermute_b32 v32, v168, v10
	ds_bpermute_b32 v29, v168, v8
	ds_bpermute_b32 v33, v168, v11
	ds_bpermute_b32 v23, v168, v9
	v_mov_b32_e32 v28, v11
	s_waitcnt lgkmcnt(3)
	v_cndmask_b32_e64 v11, v32, -v32, s[40:41]
	s_waitcnt lgkmcnt(2)
	v_cndmask_b32_e64 v30, v29, -v29, s[40:41]
	s_waitcnt lgkmcnt(1)
	v_cndmask_b32_e64 v29, v33, -v33, s[40:41]
	s_waitcnt lgkmcnt(0)
	v_cndmask_b32_e64 v31, v23, -v23, s[40:41]
	s_waitcnt vmcnt(1)
	v_pk_mul_f32 v[12:13], v[12:13], v[30:31]
	s_waitcnt vmcnt(0)
	v_mul_f32_e32 v10, v10, v26
	v_mul_f32_e32 v26, v14, v11
	v_mov_b32_e32 v14, v27
	v_pk_mul_f32 v[14:15], v[28:29], v[14:15]
	v_pk_fma_f32 v[8:9], v[8:9], v[24:25], v[12:13]
	v_mov_b32_e32 v11, v14
	v_mov_b32_e32 v27, v15
	v_pk_add_f32 v[10:11], v[10:11], v[26:27]

.LBB0_556:
	s_or_b64 exec, exec, s[4:5]
	v_mov_b64_e32 v[12:13], v[84:85]
	v_mov_b64_e32 v[14:15], v[86:87]
	s_waitcnt lgkmcnt(0)
	v_mul_f32_e32 v9, v5, v5
	v_fmac_f32_e32 v9, v4, v4
	v_pk_mul_f32 v[10:11], v[6:7], v[6:7]
	v_pk_mul_f32 v[16:17], v[12:13], v[12:13]
	v_add_f32_e32 v9, v10, v9
	v_add_f32_e32 v9, v11, v9
	v_add_f32_e32 v9, v9, v16
	v_add_f32_e32 v9, v17, v9
	v_mov_b64_e32 v[16:17], v[68:69]
	v_mov_b64_e32 v[18:19], v[70:71]
	v_pk_mul_f32 v[10:11], v[14:15], v[14:15]
	s_nop 0
	v_add_f32_e32 v9, v10, v9
	v_add_f32_e32 v9, v11, v9
	s_nop 1
	v_mov_b32_e32 v11, 0
	s_waitcnt lgkmcnt(0)
	v_add_f32_dpp v9, v9, v9 quad_perm:[1,0,3,2] row_mask:0xf bank_mask:0xf
	s_nop 1
	s_waitcnt lgkmcnt(0)
	v_add_f32_dpp v9, v9, v9 quad_perm:[2,3,0,1] row_mask:0xf bank_mask:0xf
	s_nop 1
	s_waitcnt lgkmcnt(0)
	v_add_f32_dpp v22, v9, v9 row_half_mirror row_mask:0xf bank_mask:0xf
	ds_bpermute_b32 v23, v171, v22
	v_mov_b32_e32 v9, 0
	v_mov_b32_e32 v10, 0
	s_and_saveexec_b64 s[4:5], s[38:39]
	s_cbranch_execz .LBB0_558
.LBB0_558:
	s_or_b64 exec, exec, s[4:5]
	v_mov_b64_e32 v[8:9], v[72:73]
	v_mov_b64_e32 v[10:11], v[74:75]
	s_waitcnt lgkmcnt(0)
	v_add_f32_e32 v22, v22, v23
	v_fmamk_f32 v22, v22, 0x3c2aaaab, v1
	v_mul_f32_e32 v23, 0x4b800000, v22
	v_cmp_gt_f32_e64 s[4:5], s29, v22
	s_and_b64 vcc, exec, s[0:1]
	s_nop 0
	v_cndmask_b32_e64 v22, v22, v23, s[4:5]
	v_rsq_f32_e32 v22, v22
	s_nop 0
	v_mul_f32_e32 v23, 0x45800000, v22
	v_cndmask_b32_e64 v22, v22, v23, s[4:5]
	v_pk_mul_f32 v[12:13], v[12:13], v[22:23] op_sel_hi:[1,0]
	v_pk_mul_f32 v[14:15], v[14:15], v[22:23] op_sel_hi:[1,0]
	v_pk_mul_f32 v[8:9], v[12:13], v[8:9]
	v_pk_mul_f32 v[10:11], v[14:15], v[10:11]
	s_cbranch_vccnz .LBB0_560
	v_add_u32_e32 v12, s34, v20
	v_ashrrev_i32_e32 v12, 6, v12
	v_cndmask_b32_e64 v12, v176, v12, s[2:3]
	v_lshlrev_b32_e32 v12, 3, v12
	v_ashrrev_i32_e32 v13, 31, v12
	v_lshlrev_b64 v[12:13], 2, v[12:13]
	v_lshl_add_u64 v[24:25], v[158:159], 0, v[12:13]
	v_lshl_add_u64 v[12:13], v[160:161], 0, v[12:13]
	global_load_dwordx4 v[12:15], v[12:13], off
	s_nop 0
	global_load_dwordx4 v[24:27], v[24:25], off
	ds_bpermute_b32 v32, v168, v10
	ds_bpermute_b32 v29, v168, v8
	ds_bpermute_b32 v33, v168, v11
	ds_bpermute_b32 v23, v168, v9
	v_mov_b32_e32 v28, v11
	s_waitcnt lgkmcnt(3)
	v_cndmask_b32_e64 v11, v32, -v32, s[40:41]
	s_waitcnt lgkmcnt(2)
	v_cndmask_b32_e64 v30, v29, -v29, s[40:41]
	s_waitcnt lgkmcnt(1)
	v_cndmask_b32_e64 v29, v33, -v33, s[40:41]
	s_waitcnt lgkmcnt(0)
	v_cndmask_b32_e64 v31, v23, -v23, s[40:41]
	s_waitcnt vmcnt(1)
	v_pk_mul_f32 v[12:13], v[12:13], v[30:31]
	s_waitcnt vmcnt(0)
	v_mul_f32_e32 v10, v10, v26
	v_mul_f32_e32 v26, v14, v11
	v_mov_b32_e32 v14, v27
	v_pk_mul_f32 v[14:15], v[28:29], v[14:15]
	v_pk_fma_f32 v[8:9], v[8:9], v[24:25], v[12:13]
	v_mov_b32_e32 v11, v14
	v_mov_b32_e32 v27, v15
	v_pk_add_f32 v[10:11], v[10:11], v[26:27]
